# P5/P8: first two vmcnt waits of each tile's first K-iteration removed (next-tile stages are already guaranteed by the epilogue's counted waits) so LA..LC overlap the epilogue store drain
# speedup vs baseline: 1.0081x; 1.0014x over previous
.LBB0_876:
	s_add_u32 s10, s22, 0x1c00000
	s_addc_u32 s11, s23, 0
	s_add_u32 s51, s22, 0x18ba4000
	v_readlane_b32 s31, v246, 0
	s_addc_u32 s52, s23, 0
	s_add_i32 s19, s31, 0x18000
	s_and_b32 s53, s9, 3
	s_add_i32 s54, s19, s5
	s_mov_b64 s[12:13], 0x80
	s_lshl_b32 s9, s4, 13
	s_lshl_b32 s18, s53, 12
	v_lshl_add_u64 v[6:7], v[6:7], 0, s[12:13]
	s_mov_b32 m0, s54
	s_add_i32 s55, s54, 0x2000
	s_add_i32 s56, s45, 0x8000
	s_add_i32 s57, s45, 0xa000
	global_load_lds_dwordx4 v[6:7], off
	v_lshl_add_u64 v[4:5], v[4:5], 0, s[12:13]
	s_mov_b32 m0, s55
	s_add_u32 s16, s28, 0x40080
	global_load_lds_dwordx4 v[4:5], off
	v_lshl_add_u64 v[2:3], v[2:3], 0, s[12:13]
	s_mov_b32 m0, s56
	s_addc_u32 s17, s29, 0
	s_add_i32 s25, s31, 0x1c000
	global_load_lds_dwordx4 v[2:3], off
	v_lshl_add_u64 v[0:1], v[0:1], 0, s[12:13]
	s_mov_b32 m0, s57
	s_add_i32 s58, s25, s5
	global_load_lds_dwordx4 v[0:1], off
	v_lshl_add_u64 v[0:1], s[16:17], 0, v[160:161]
	s_mov_b32 m0, s58
	s_add_i32 s59, s58, 0x2000
	global_load_lds_dwordx4 v[0:1], off
	v_lshl_add_u64 v[0:1], s[16:17], 0, v[162:163]
	s_mov_b32 m0, s59
	v_lshlrev_b32_e32 v5, 6, v202
	global_load_lds_dwordx4 v[0:1], off
	s_waitcnt vmcnt(8)
	s_barrier
	v_bfe_u32 v0, v202, 4, 2
	v_and_b32_e32 v1, 15, v202
	s_waitcnt vmcnt(0)
	v_lshl_or_b32 v184, s4, 6, v1
	v_lshlrev_b32_e32 v3, 4, v0
	s_movk_i32 s4, 0x3c0
	v_lshlrev_b32_e32 v2, 3, v0
	v_lshl_or_b32 v1, v1, 6, v3
	v_and_or_b32 v3, v5, s4, v3
	v_cmp_eq_u32_e64 s[4:5], 0, v0
	v_lshlrev_b32_e32 v0, 8, v202
	v_lshl_or_b32 v185, s53, 6, v2
	v_and_b32_e32 v0, 0xffff8000, v0
	v_lshlrev_b32_e32 v2, 11, v10
	v_or3_b32 v0, v8, v0, v2
	v_add_u32_e32 v164, v0, v9
	v_lshlrev_b32_e32 v0, 4, v11
	v_lshlrev_b32_e32 v4, 2, v202
	v_and_b32_e32 v0, 0xffff8000, v0
	v_and_b32_e32 v4, 32, v4
	s_waitcnt vmcnt(6)
	v_or3_b32 v0, v8, v0, v2
	v_bitop3_b32 v1, v1, s9, v4 bitop3:0xde
	v_bitop3_b32 v3, s18, v3, v4 bitop3:0xf6
	s_mov_b32 s9, 0
	v_readlane_b32 s16, v246, 1
	v_add_u32_e32 v166, v0, v9
	v_mbcnt_lo_u32_b32 v0, -1, 0
	v_readlane_b32 s17, v246, 2
	s_ashr_i32 s60, s16, 31
	s_mov_b32 s61, s16
	s_ashr_i32 s62, s30, 31
	s_lshr_b32 s63, s33, 1
	v_mov_b32_e32 v165, v161
	v_mov_b32_e32 v167, v161
	v_mov_b64_e32 v[168:169], s[8:9]
	v_add_u32_e32 v186, s14, v3
	v_add_u32_e32 v187, s31, v1
	v_add_u32_e32 v188, s15, v3
	v_add_u32_e32 v189, s19, v3
	v_add_u32_e32 v190, s25, v3
	v_mbcnt_hi_u32_b32 v191, -1, v0
	s_barrier
	s_waitcnt vmcnt(0)
	s_branch .LBB0_878

.LBB0_882:
	s_xor_b64 s[18:19], s[36:37], -1
	s_and_b64 s[30:31], s[36:37], exec
	s_cselect_b32 s25, s15, s27
	s_cselect_b32 s34, s14, s26
	s_cselect_b32 s36, s17, s29
	s_cselect_b32 s37, s16, s28
	s_add_u32 s26, s26, 0x40080
	s_addc_u32 s27, s27, 0
	s_add_u32 s38, s28, 0x100
	s_addc_u32 s39, s29, 0
	s_mov_b32 s40, -2
	s_waitcnt lgkmcnt(0)
	ds_read_b128 v[128:131], v186
	ds_read_b128 v[132:135], v186 offset:1024
	ds_read_b128 v[136:139], v186 offset:2048
	ds_read_b128 v[140:143], v186 offset:3072
	s_add_u32 s28, s26, 0xfffc0080
	s_addc_u32 s29, s27, -1
	s_cmp_eq_u32 s40, 12
	s_cselect_b32 s31, s25, s29
	s_cselect_b32 s30, s34, s28
	s_cselect_b32 s29, s36, s39
	s_cselect_b32 s28, s37, s38
	v_lshl_add_u64 v[182:183], s[26:27], 0, v[164:165]
	s_add_i32 m0, s45, 0xc000
	ds_read_b128 v[144:147], v187
	ds_read_b128 v[148:151], v187 offset:1024
	ds_read_b128 v[152:155], v187 offset:2048
	ds_read_b128 v[156:159], v187 offset:3072
	ds_read_b128 v[170:173], v187 offset:4096
	ds_read_b128 v[174:177], v187 offset:5120
	ds_read_b128 v[178:181], v187 offset:6144
	ds_read_b128 v[192:195], v187 offset:7168
	global_load_lds_dwordx4 v[182:183], off
	v_lshl_add_u64 v[182:183], s[26:27], 0, v[166:167]
	s_add_i32 m0, s45, 0xe000
	s_nop 0
	global_load_lds_dwordx4 v[182:183], off
	ds_read_b128 v[196:199], v188
	ds_read_b128 v[204:207], v188 offset:1024
	ds_read_b128 v[208:211], v188 offset:2048
	ds_read_b128 v[212:215], v188 offset:3072
	s_waitcnt lgkmcnt(0)
	s_nop 0
	s_barrier
	s_setprio 1
	v_mfma_f32_16x16x32_bf16 v[124:127], v[128:131], v[144:147], 0
	v_mfma_f32_16x16x32_bf16 v[120:123], v[136:139], v[144:147], 0
	v_mfma_f32_16x16x32_bf16 v[108:111], v[128:131], v[152:155], 0
	v_mfma_f32_16x16x32_bf16 v[104:107], v[136:139], v[152:155], 0
	v_mfma_f32_16x16x32_bf16 v[92:95], v[128:131], v[170:173], 0
	v_mfma_f32_16x16x32_bf16 v[88:91], v[136:139], v[170:173], 0
	v_mfma_f32_16x16x32_bf16 v[76:79], v[128:131], v[178:181], 0
	v_mfma_f32_16x16x32_bf16 v[72:75], v[136:139], v[178:181], 0
	v_mfma_f32_16x16x32_bf16 v[124:127], v[132:135], v[148:151], v[124:127]
	v_mfma_f32_16x16x32_bf16 v[120:123], v[140:143], v[148:151], v[120:123]
	v_mfma_f32_16x16x32_bf16 v[108:111], v[132:135], v[156:159], v[108:111]
	v_mfma_f32_16x16x32_bf16 v[104:107], v[140:143], v[156:159], v[104:107]
	v_mfma_f32_16x16x32_bf16 v[92:95], v[132:135], v[174:177], v[92:95]
	v_mfma_f32_16x16x32_bf16 v[88:91], v[140:143], v[174:177], v[88:91]
	v_mfma_f32_16x16x32_bf16 v[76:79], v[132:135], v[192:195], v[76:79]
	v_mfma_f32_16x16x32_bf16 v[72:75], v[140:143], v[192:195], v[72:75]
	v_mfma_f32_16x16x32_bf16 v[116:119], v[196:199], v[144:147], 0
	v_mfma_f32_16x16x32_bf16 v[112:115], v[208:211], v[144:147], 0
	v_mfma_f32_16x16x32_bf16 v[100:103], v[196:199], v[152:155], 0
	v_mfma_f32_16x16x32_bf16 v[96:99], v[208:211], v[152:155], 0
	v_mfma_f32_16x16x32_bf16 v[84:87], v[196:199], v[170:173], 0
	v_mfma_f32_16x16x32_bf16 v[80:83], v[208:211], v[170:173], 0
	v_mfma_f32_16x16x32_bf16 v[68:71], v[196:199], v[178:181], 0
	v_mfma_f32_16x16x32_bf16 v[64:67], v[208:211], v[178:181], 0
	v_mfma_f32_16x16x32_bf16 v[116:119], v[204:207], v[148:151], v[116:119]
	v_mfma_f32_16x16x32_bf16 v[112:115], v[212:215], v[148:151], v[112:115]
	v_mfma_f32_16x16x32_bf16 v[100:103], v[204:207], v[156:159], v[100:103]
	v_mfma_f32_16x16x32_bf16 v[96:99], v[212:215], v[156:159], v[96:99]
	v_mfma_f32_16x16x32_bf16 v[84:87], v[204:207], v[174:177], v[84:87]
	v_mfma_f32_16x16x32_bf16 v[80:83], v[212:215], v[174:177], v[80:83]
	v_mfma_f32_16x16x32_bf16 v[68:71], v[204:207], v[192:195], v[68:71]
	v_mfma_f32_16x16x32_bf16 v[64:67], v[212:215], v[192:195], v[64:67]
	s_setprio 0
	s_barrier
	v_lshl_or_b32 v203, s65, 8, v185
	v_lshlrev_b32_e32 v203, 1, v203
	v_lshl_add_u32 v247, s24, 8, v184
	v_lshl_add_u32 v203, v247, 11, v203
	s_add_u32 s74, s10, 0x8000
	s_addc_u32 s75, s11, 0
	s_add_u32 s76, s10, 0x10000
	s_addc_u32 s77, s11, 0
	s_add_u32 s78, s10, 0x18000
	s_addc_u32 s79, s11, 0
	global_load_dwordx4 v[220:223], v203, s[10:11]
	global_load_dwordx4 v[224:227], v203, s[10:11] offset:64
	global_load_dwordx4 v[228:231], v203, s[74:75]
	global_load_dwordx4 v[232:235], v203, s[74:75] offset:64
	global_load_dwordx4 v[236:239], v203, s[76:77]
	global_load_dwordx4 v[240:243], v203, s[76:77] offset:64
	global_load_dwordx4 v[252:255], v203, s[78:79]
	ds_read_b128 v[144:147], v187 offset:16384
	ds_read_b128 v[148:151], v187 offset:17408
	ds_read_b128 v[152:155], v187 offset:18432
	ds_read_b128 v[156:159], v187 offset:19456
	ds_read_b128 v[170:173], v187 offset:20480
	ds_read_b128 v[174:177], v187 offset:21504
	ds_read_b128 v[178:181], v187 offset:22528
	ds_read_b128 v[192:195], v187 offset:23552
	s_mov_b32 m0, s43
	v_lshl_add_u64 v[182:183], s[28:29], 0, v[160:161]
	global_load_lds_dwordx4 v[182:183], off
	v_lshl_add_u64 v[200:201], s[28:29], 0, v[162:163]
	s_mov_b32 m0, s44
	s_nop 0
	global_load_lds_dwordx4 v[200:201], off
	s_mov_b32 m0, s45
	v_lshl_add_u64 v[216:217], s[30:31], 0, v[160:161]
	global_load_lds_dwordx4 v[216:217], off
	v_lshl_add_u64 v[218:219], s[30:31], 0, v[162:163]
	s_mov_b32 m0, s46
	s_nop 0
	global_load_lds_dwordx4 v[218:219], off
	s_add_u32 s66, s28, 0x40000
	s_addc_u32 s67, s29, 0
	s_mov_b32 m0, s47
	v_lshl_add_u64 v[248:249], s[66:67], 0, v[160:161]
	global_load_lds_dwordx4 v[248:249], off
	v_lshl_add_u64 v[248:249], s[66:67], 0, v[162:163]
	s_mov_b32 m0, s48
	s_nop 0
	global_load_lds_dwordx4 v[248:249], off
	s_waitcnt lgkmcnt(0)
	s_nop 0
	s_barrier
	s_setprio 1
	v_mfma_f32_16x16x32_bf16 v[60:63], v[128:131], v[144:147], 0
	v_mfma_f32_16x16x32_bf16 v[56:59], v[136:139], v[144:147], 0
	v_mfma_f32_16x16x32_bf16 v[44:47], v[128:131], v[152:155], 0
	v_mfma_f32_16x16x32_bf16 v[40:43], v[136:139], v[152:155], 0
	v_mfma_f32_16x16x32_bf16 v[28:31], v[128:131], v[170:173], 0
	v_mfma_f32_16x16x32_bf16 v[24:27], v[136:139], v[170:173], 0
	v_mfma_f32_16x16x32_bf16 v[12:15], v[128:131], v[178:181], 0
	v_mfma_f32_16x16x32_bf16 v[8:11], v[136:139], v[178:181], 0
	v_mfma_f32_16x16x32_bf16 v[60:63], v[132:135], v[148:151], v[60:63]
	v_mfma_f32_16x16x32_bf16 v[56:59], v[140:143], v[148:151], v[56:59]
	v_mfma_f32_16x16x32_bf16 v[44:47], v[132:135], v[156:159], v[44:47]
	v_mfma_f32_16x16x32_bf16 v[40:43], v[140:143], v[156:159], v[40:43]
	v_mfma_f32_16x16x32_bf16 v[28:31], v[132:135], v[174:177], v[28:31]
	v_mfma_f32_16x16x32_bf16 v[24:27], v[140:143], v[174:177], v[24:27]
	v_mfma_f32_16x16x32_bf16 v[12:15], v[132:135], v[192:195], v[12:15]
	v_mfma_f32_16x16x32_bf16 v[8:11], v[140:143], v[192:195], v[8:11]
	v_mfma_f32_16x16x32_bf16 v[52:55], v[196:199], v[144:147], 0
	v_mfma_f32_16x16x32_bf16 v[48:51], v[208:211], v[144:147], 0
	v_mfma_f32_16x16x32_bf16 v[36:39], v[196:199], v[152:155], 0
	v_mfma_f32_16x16x32_bf16 v[32:35], v[208:211], v[152:155], 0
	v_mfma_f32_16x16x32_bf16 v[20:23], v[196:199], v[170:173], 0
	v_mfma_f32_16x16x32_bf16 v[16:19], v[208:211], v[170:173], 0
	v_mfma_f32_16x16x32_bf16 v[4:7], v[196:199], v[178:181], 0
	v_mfma_f32_16x16x32_bf16 v[0:3], v[208:211], v[178:181], 0
	v_mfma_f32_16x16x32_bf16 v[52:55], v[204:207], v[148:151], v[52:55]
	v_mfma_f32_16x16x32_bf16 v[48:51], v[212:215], v[148:151], v[48:51]
	v_mfma_f32_16x16x32_bf16 v[36:39], v[204:207], v[156:159], v[36:39]
	v_mfma_f32_16x16x32_bf16 v[32:35], v[212:215], v[156:159], v[32:35]
	v_mfma_f32_16x16x32_bf16 v[20:23], v[204:207], v[174:177], v[20:23]
	v_mfma_f32_16x16x32_bf16 v[16:19], v[212:215], v[174:177], v[16:19]
	v_mfma_f32_16x16x32_bf16 v[4:7], v[204:207], v[192:195], v[4:7]
	v_mfma_f32_16x16x32_bf16 v[0:3], v[212:215], v[192:195], v[0:3]
	s_setprio 0
	s_barrier
	ds_read_b128 v[128:131], v189
	ds_read_b128 v[132:135], v189 offset:1024
	ds_read_b128 v[136:139], v189 offset:2048
	ds_read_b128 v[140:143], v189 offset:3072
	s_add_u32 s30, s30, 0x40000
	s_addc_u32 s31, s31, 0
	s_mov_b32 m0, s49
	v_lshl_add_u64 v[196:197], s[30:31], 0, v[160:161]
	ds_read_b128 v[144:147], v187 offset:32768
	ds_read_b128 v[148:151], v187 offset:33792
	ds_read_b128 v[152:155], v187 offset:34816
	ds_read_b128 v[156:159], v187 offset:35840
	ds_read_b128 v[170:173], v187 offset:36864
	ds_read_b128 v[174:177], v187 offset:37888
	ds_read_b128 v[178:181], v187 offset:38912
	ds_read_b128 v[192:195], v187 offset:39936
	global_load_lds_dwordx4 v[196:197], off
	v_lshl_add_u64 v[196:197], s[30:31], 0, v[162:163]
	s_mov_b32 m0, s50
	s_nop 0
	global_load_lds_dwordx4 v[196:197], off
	ds_read_b128 v[196:199], v190
	ds_read_b128 v[204:207], v190 offset:1024
	ds_read_b128 v[208:211], v190 offset:2048
	ds_read_b128 v[212:215], v190 offset:3072
	s_waitcnt lgkmcnt(0)
	s_waitcnt vmcnt(15)
	s_barrier
	s_setprio 1
	v_mfma_f32_16x16x32_bf16 v[124:127], v[128:131], v[144:147], v[124:127]
	v_mfma_f32_16x16x32_bf16 v[120:123], v[136:139], v[144:147], v[120:123]
	v_mfma_f32_16x16x32_bf16 v[108:111], v[128:131], v[152:155], v[108:111]
	v_mfma_f32_16x16x32_bf16 v[104:107], v[136:139], v[152:155], v[104:107]
	v_mfma_f32_16x16x32_bf16 v[92:95], v[128:131], v[170:173], v[92:95]
	v_mfma_f32_16x16x32_bf16 v[88:91], v[136:139], v[170:173], v[88:91]
	v_mfma_f32_16x16x32_bf16 v[76:79], v[128:131], v[178:181], v[76:79]
	v_mfma_f32_16x16x32_bf16 v[72:75], v[136:139], v[178:181], v[72:75]
	v_mfma_f32_16x16x32_bf16 v[124:127], v[132:135], v[148:151], v[124:127]
	v_mfma_f32_16x16x32_bf16 v[120:123], v[140:143], v[148:151], v[120:123]
	v_mfma_f32_16x16x32_bf16 v[108:111], v[132:135], v[156:159], v[108:111]
	v_mfma_f32_16x16x32_bf16 v[104:107], v[140:143], v[156:159], v[104:107]
	v_mfma_f32_16x16x32_bf16 v[92:95], v[132:135], v[174:177], v[92:95]
	v_mfma_f32_16x16x32_bf16 v[88:91], v[140:143], v[174:177], v[88:91]
	v_mfma_f32_16x16x32_bf16 v[76:79], v[132:135], v[192:195], v[76:79]
	v_mfma_f32_16x16x32_bf16 v[72:75], v[140:143], v[192:195], v[72:75]
	v_mfma_f32_16x16x32_bf16 v[116:119], v[196:199], v[144:147], v[116:119]
	v_mfma_f32_16x16x32_bf16 v[112:115], v[208:211], v[144:147], v[112:115]
	v_mfma_f32_16x16x32_bf16 v[100:103], v[196:199], v[152:155], v[100:103]
	v_mfma_f32_16x16x32_bf16 v[96:99], v[208:211], v[152:155], v[96:99]
	v_mfma_f32_16x16x32_bf16 v[84:87], v[196:199], v[170:173], v[84:87]
	v_mfma_f32_16x16x32_bf16 v[80:83], v[208:211], v[170:173], v[80:83]
	v_mfma_f32_16x16x32_bf16 v[68:71], v[196:199], v[178:181], v[68:71]
	v_mfma_f32_16x16x32_bf16 v[64:67], v[208:211], v[178:181], v[64:67]
	v_mfma_f32_16x16x32_bf16 v[116:119], v[204:207], v[148:151], v[116:119]
	v_mfma_f32_16x16x32_bf16 v[112:115], v[212:215], v[148:151], v[112:115]
	v_mfma_f32_16x16x32_bf16 v[100:103], v[204:207], v[156:159], v[100:103]
	v_mfma_f32_16x16x32_bf16 v[96:99], v[212:215], v[156:159], v[96:99]
	v_mfma_f32_16x16x32_bf16 v[84:87], v[204:207], v[174:177], v[84:87]
	v_mfma_f32_16x16x32_bf16 v[80:83], v[212:215], v[174:177], v[80:83]
	v_mfma_f32_16x16x32_bf16 v[68:71], v[204:207], v[192:195], v[68:71]
	v_mfma_f32_16x16x32_bf16 v[64:67], v[212:215], v[192:195], v[64:67]
	s_setprio 0
	s_barrier
	ds_read_b128 v[144:147], v187 offset:49152
	ds_read_b128 v[148:151], v187 offset:50176
	ds_read_b128 v[152:155], v187 offset:51200
	ds_read_b128 v[156:159], v187 offset:52224
	ds_read_b128 v[170:173], v187 offset:53248
	ds_read_b128 v[174:177], v187 offset:54272
	ds_read_b128 v[178:181], v187 offset:55296
	ds_read_b128 v[192:195], v187 offset:56320
	s_mov_b32 m0, s54
	v_lshl_add_u64 v[182:183], v[182:183], 0, s[12:13]
	global_load_lds_dwordx4 v[182:183], off
	v_lshl_add_u64 v[182:183], v[200:201], 0, s[12:13]
	s_mov_b32 m0, s55
	s_nop 0
	global_load_lds_dwordx4 v[182:183], off
	s_mov_b32 m0, s56
	v_lshl_add_u64 v[182:183], v[216:217], 0, s[12:13]
	global_load_lds_dwordx4 v[182:183], off
	v_lshl_add_u64 v[182:183], v[218:219], 0, s[12:13]
	s_mov_b32 m0, s57
	s_nop 0
	global_load_lds_dwordx4 v[182:183], off
	s_add_u32 s28, s28, 0x40080
	s_addc_u32 s29, s29, 0
	s_mov_b32 m0, s58
	v_lshl_add_u64 v[248:249], s[28:29], 0, v[160:161]
	global_load_lds_dwordx4 v[248:249], off
	v_lshl_add_u64 v[248:249], s[28:29], 0, v[162:163]
	s_mov_b32 m0, s59
	s_nop 0
	global_load_lds_dwordx4 v[248:249], off
	s_waitcnt lgkmcnt(0)
	s_waitcnt vmcnt(8)
	s_barrier
	s_setprio 1
	v_mfma_f32_16x16x32_bf16 v[60:63], v[128:131], v[144:147], v[60:63]
	v_mfma_f32_16x16x32_bf16 v[56:59], v[136:139], v[144:147], v[56:59]
	v_mfma_f32_16x16x32_bf16 v[44:47], v[128:131], v[152:155], v[44:47]
	v_mfma_f32_16x16x32_bf16 v[40:43], v[136:139], v[152:155], v[40:43]
	v_mfma_f32_16x16x32_bf16 v[28:31], v[128:131], v[170:173], v[28:31]
	v_mfma_f32_16x16x32_bf16 v[24:27], v[136:139], v[170:173], v[24:27]
	v_mfma_f32_16x16x32_bf16 v[12:15], v[128:131], v[178:181], v[12:15]
	v_mfma_f32_16x16x32_bf16 v[8:11], v[136:139], v[178:181], v[8:11]
	v_mfma_f32_16x16x32_bf16 v[60:63], v[132:135], v[148:151], v[60:63]
	v_mfma_f32_16x16x32_bf16 v[56:59], v[140:143], v[148:151], v[56:59]
	v_mfma_f32_16x16x32_bf16 v[44:47], v[132:135], v[156:159], v[44:47]
	v_mfma_f32_16x16x32_bf16 v[40:43], v[140:143], v[156:159], v[40:43]
	v_mfma_f32_16x16x32_bf16 v[28:31], v[132:135], v[174:177], v[28:31]
	v_mfma_f32_16x16x32_bf16 v[24:27], v[140:143], v[174:177], v[24:27]
	v_mfma_f32_16x16x32_bf16 v[12:15], v[132:135], v[192:195], v[12:15]
	v_mfma_f32_16x16x32_bf16 v[8:11], v[140:143], v[192:195], v[8:11]
	v_mfma_f32_16x16x32_bf16 v[52:55], v[196:199], v[144:147], v[52:55]
	v_mfma_f32_16x16x32_bf16 v[48:51], v[208:211], v[144:147], v[48:51]
	v_mfma_f32_16x16x32_bf16 v[36:39], v[196:199], v[152:155], v[36:39]
	v_mfma_f32_16x16x32_bf16 v[32:35], v[208:211], v[152:155], v[32:35]
	v_mfma_f32_16x16x32_bf16 v[20:23], v[196:199], v[170:173], v[20:23]
	v_mfma_f32_16x16x32_bf16 v[16:19], v[208:211], v[170:173], v[16:19]
	v_mfma_f32_16x16x32_bf16 v[4:7], v[196:199], v[178:181], v[4:7]
	v_mfma_f32_16x16x32_bf16 v[0:3], v[208:211], v[178:181], v[0:3]
	v_mfma_f32_16x16x32_bf16 v[52:55], v[204:207], v[148:151], v[52:55]
	v_mfma_f32_16x16x32_bf16 v[48:51], v[212:215], v[148:151], v[48:51]
	v_mfma_f32_16x16x32_bf16 v[36:39], v[204:207], v[156:159], v[36:39]
	v_mfma_f32_16x16x32_bf16 v[32:35], v[212:215], v[156:159], v[32:35]
	v_mfma_f32_16x16x32_bf16 v[20:23], v[204:207], v[174:177], v[20:23]
	v_mfma_f32_16x16x32_bf16 v[16:19], v[212:215], v[174:177], v[16:19]
	v_mfma_f32_16x16x32_bf16 v[4:7], v[204:207], v[192:195], v[4:7]
	v_mfma_f32_16x16x32_bf16 v[0:3], v[212:215], v[192:195], v[0:3]
	s_setprio 0
	s_add_i32 s40, s40, 2
	s_add_u32 s26, s26, 0x100
	s_addc_u32 s27, s27, 0
	s_add_u32 s38, s38, 0x100
	s_addc_u32 s39, s39, 0
	s_cmp_gt_u32 s40, 13
	s_barrier

.LBB0_1121:
	s_add_u32 s8, s22, 0x1c00000
	s_addc_u32 s9, s23, 0
	s_add_u32 s48, s22, 0x18db4000
	v_readlane_b32 s29, v246, 0
	s_addc_u32 s49, s23, 0
	s_add_i32 s19, s29, 0x18000
	s_and_b32 s50, s10, 3
	s_add_i32 s51, s19, s5
	s_mov_b64 s[10:11], 0x80
	s_lshl_b32 s16, s4, 13
	s_lshl_b32 s17, s50, 12
	v_lshl_add_u64 v[6:7], v[6:7], 0, s[10:11]
	s_mov_b32 m0, s51
	s_add_i32 s52, s51, 0x2000
	s_add_i32 s53, s42, 0x8000
	s_add_i32 s54, s42, 0xa000
	global_load_lds_dwordx4 v[6:7], off
	v_lshl_add_u64 v[4:5], v[4:5], 0, s[10:11]
	s_mov_b32 m0, s52
	s_add_u32 s14, s26, 0x20080
	global_load_lds_dwordx4 v[4:5], off
	v_lshl_add_u64 v[2:3], v[2:3], 0, s[10:11]
	s_mov_b32 m0, s53
	s_addc_u32 s15, s27, 0
	s_add_i32 s28, s29, 0x1c000
	global_load_lds_dwordx4 v[2:3], off
	v_lshl_add_u64 v[0:1], v[0:1], 0, s[10:11]
	s_mov_b32 m0, s54
	s_add_i32 s55, s28, s5
	global_load_lds_dwordx4 v[0:1], off
	v_lshl_add_u64 v[0:1], s[14:15], 0, v[160:161]
	s_mov_b32 m0, s55
	s_add_i32 s56, s55, 0x2000
	global_load_lds_dwordx4 v[0:1], off
	v_lshl_add_u64 v[0:1], s[14:15], 0, v[162:163]
	s_mov_b32 m0, s56
	v_lshlrev_b32_e32 v5, 6, v202
	global_load_lds_dwordx4 v[0:1], off
	s_waitcnt vmcnt(8)
	s_barrier
	v_bfe_u32 v0, v202, 4, 2
	v_and_b32_e32 v1, 15, v202
	s_waitcnt vmcnt(0)
	v_lshl_or_b32 v184, s4, 6, v1
	v_lshlrev_b32_e32 v3, 4, v0
	s_movk_i32 s4, 0x3c0
	v_lshlrev_b32_e32 v2, 3, v0
	v_lshl_or_b32 v1, v1, 6, v3
	v_and_or_b32 v3, v5, s4, v3
	v_cmp_eq_u32_e64 s[4:5], 0, v0
	v_lshlrev_b32_e32 v0, 7, v202
	v_lshl_or_b32 v185, s50, 6, v2
	v_and_b32_e32 v0, 0xffffc000, v0
	v_lshlrev_b32_e32 v2, 10, v10
	v_or3_b32 v0, v8, v0, v2
	v_add_u32_e32 v164, v0, v9
	v_lshlrev_b32_e32 v0, 3, v11
	v_lshlrev_b32_e32 v4, 2, v202
	v_and_b32_e32 v0, 0xffffc000, v0
	v_and_b32_e32 v4, 32, v4
	s_waitcnt vmcnt(6)
	v_or3_b32 v0, v8, v0, v2
	v_bitop3_b32 v1, v1, s16, v4 bitop3:0xde
	v_bitop3_b32 v3, s17, v3, v4 bitop3:0xf6
	v_readlane_b32 s14, v246, 1
	v_add_u32_e32 v166, v0, v9
	v_mbcnt_lo_u32_b32 v0, -1, 0
	s_mov_b32 s57, 0
	v_readlane_b32 s15, v246, 2
	s_ashr_i32 s58, s14, 31
	s_mov_b32 s59, s14
	s_ashr_i32 s60, s30, 31
	v_mov_b32_e32 v165, v161
	v_mov_b32_e32 v167, v161
	v_mov_b64_e32 v[168:169], 0x20f
	s_movk_i32 s61, 0x43
	v_add_u32_e32 v186, s12, v3
	v_add_u32_e32 v187, s29, v1
	v_add_u32_e32 v188, s13, v3
	v_add_u32_e32 v189, s19, v3
	v_add_u32_e32 v190, s28, v3
	v_mbcnt_hi_u32_b32 v191, -1, v0
	s_barrier
	s_waitcnt vmcnt(0)
	s_branch .LBB0_1123

.LBB0_1127:
	s_xor_b64 s[16:17], s[34:35], -1
	s_and_b64 s[28:29], s[34:35], exec
	s_cselect_b32 s19, s13, s25
	s_cselect_b32 s30, s12, s24
	s_cselect_b32 s34, s15, s27
	s_cselect_b32 s35, s14, s26
	s_add_u32 s24, s24, 0x20080
	s_addc_u32 s25, s25, 0
	s_add_u32 s36, s26, 0x100
	s_addc_u32 s37, s27, 0
	s_mov_b32 s38, -2
	s_waitcnt lgkmcnt(0)
	ds_read_b128 v[128:131], v186
	ds_read_b128 v[132:135], v186 offset:1024
	ds_read_b128 v[136:139], v186 offset:2048
	ds_read_b128 v[140:143], v186 offset:3072
	s_add_u32 s26, s24, 0xfffe0080
	s_addc_u32 s27, s25, -1
	s_cmp_eq_u32 s38, 4
	s_cselect_b32 s29, s19, s27
	s_cselect_b32 s28, s30, s26
	s_cselect_b32 s27, s34, s37
	s_cselect_b32 s26, s35, s36
	v_lshl_add_u64 v[182:183], s[24:25], 0, v[164:165]
	s_add_i32 m0, s42, 0xc000
	ds_read_b128 v[144:147], v187
	ds_read_b128 v[148:151], v187 offset:1024
	ds_read_b128 v[152:155], v187 offset:2048
	ds_read_b128 v[156:159], v187 offset:3072
	ds_read_b128 v[170:173], v187 offset:4096
	ds_read_b128 v[174:177], v187 offset:5120
	ds_read_b128 v[178:181], v187 offset:6144
	ds_read_b128 v[192:195], v187 offset:7168
	global_load_lds_dwordx4 v[182:183], off
	v_lshl_add_u64 v[182:183], s[24:25], 0, v[166:167]
	s_add_i32 m0, s42, 0xe000
	s_nop 0
	global_load_lds_dwordx4 v[182:183], off
	ds_read_b128 v[196:199], v188
	ds_read_b128 v[204:207], v188 offset:1024
	ds_read_b128 v[208:211], v188 offset:2048
	ds_read_b128 v[212:215], v188 offset:3072
	s_waitcnt lgkmcnt(0)
	s_nop 0
	s_barrier
	s_setprio 1
	v_mfma_f32_16x16x32_bf16 v[124:127], v[128:131], v[144:147], 0
	v_mfma_f32_16x16x32_bf16 v[120:123], v[136:139], v[144:147], 0
	v_mfma_f32_16x16x32_bf16 v[108:111], v[128:131], v[152:155], 0
	v_mfma_f32_16x16x32_bf16 v[104:107], v[136:139], v[152:155], 0
	v_mfma_f32_16x16x32_bf16 v[92:95], v[128:131], v[170:173], 0
	v_mfma_f32_16x16x32_bf16 v[88:91], v[136:139], v[170:173], 0
	v_mfma_f32_16x16x32_bf16 v[76:79], v[128:131], v[178:181], 0
	v_mfma_f32_16x16x32_bf16 v[72:75], v[136:139], v[178:181], 0
	v_mfma_f32_16x16x32_bf16 v[124:127], v[132:135], v[148:151], v[124:127]
	v_mfma_f32_16x16x32_bf16 v[120:123], v[140:143], v[148:151], v[120:123]
	v_mfma_f32_16x16x32_bf16 v[108:111], v[132:135], v[156:159], v[108:111]
	v_mfma_f32_16x16x32_bf16 v[104:107], v[140:143], v[156:159], v[104:107]
	v_mfma_f32_16x16x32_bf16 v[92:95], v[132:135], v[174:177], v[92:95]
	v_mfma_f32_16x16x32_bf16 v[88:91], v[140:143], v[174:177], v[88:91]
	v_mfma_f32_16x16x32_bf16 v[76:79], v[132:135], v[192:195], v[76:79]
	v_mfma_f32_16x16x32_bf16 v[72:75], v[140:143], v[192:195], v[72:75]
	v_mfma_f32_16x16x32_bf16 v[116:119], v[196:199], v[144:147], 0
	v_mfma_f32_16x16x32_bf16 v[112:115], v[208:211], v[144:147], 0
	v_mfma_f32_16x16x32_bf16 v[100:103], v[196:199], v[152:155], 0
	v_mfma_f32_16x16x32_bf16 v[96:99], v[208:211], v[152:155], 0
	v_mfma_f32_16x16x32_bf16 v[84:87], v[196:199], v[170:173], 0
	v_mfma_f32_16x16x32_bf16 v[80:83], v[208:211], v[170:173], 0
	v_mfma_f32_16x16x32_bf16 v[68:71], v[196:199], v[178:181], 0
	v_mfma_f32_16x16x32_bf16 v[64:67], v[208:211], v[178:181], 0
	v_mfma_f32_16x16x32_bf16 v[116:119], v[204:207], v[148:151], v[116:119]
	v_mfma_f32_16x16x32_bf16 v[112:115], v[212:215], v[148:151], v[112:115]
	v_mfma_f32_16x16x32_bf16 v[100:103], v[204:207], v[156:159], v[100:103]
	v_mfma_f32_16x16x32_bf16 v[96:99], v[212:215], v[156:159], v[96:99]
	v_mfma_f32_16x16x32_bf16 v[84:87], v[204:207], v[174:177], v[84:87]
	v_mfma_f32_16x16x32_bf16 v[80:83], v[212:215], v[174:177], v[80:83]
	v_mfma_f32_16x16x32_bf16 v[68:71], v[204:207], v[192:195], v[68:71]
	v_mfma_f32_16x16x32_bf16 v[64:67], v[212:215], v[192:195], v[64:67]
	s_setprio 0
	s_barrier
	v_lshl_or_b32 v203, s63, 8, v185
	v_lshlrev_b32_e32 v203, 1, v203
	v_lshl_add_u32 v247, s18, 8, v184
	v_lshl_add_u32 v203, v247, 11, v203
	s_add_u32 s74, s8, 0x8000
	s_addc_u32 s75, s9, 0
	s_add_u32 s76, s8, 0x10000
	s_addc_u32 s77, s9, 0
	s_add_u32 s78, s8, 0x18000
	s_addc_u32 s79, s9, 0
	global_load_dwordx4 v[220:223], v203, s[8:9]
	global_load_dwordx4 v[224:227], v203, s[8:9] offset:64
	global_load_dwordx4 v[228:231], v203, s[74:75]
	global_load_dwordx4 v[232:235], v203, s[74:75] offset:64
	global_load_dwordx4 v[236:239], v203, s[76:77]
	global_load_dwordx4 v[240:243], v203, s[76:77] offset:64
	global_load_dwordx4 v[252:255], v203, s[78:79]
	ds_read_b128 v[144:147], v187 offset:16384
	ds_read_b128 v[148:151], v187 offset:17408
	ds_read_b128 v[152:155], v187 offset:18432
	ds_read_b128 v[156:159], v187 offset:19456
	ds_read_b128 v[170:173], v187 offset:20480
	ds_read_b128 v[174:177], v187 offset:21504
	ds_read_b128 v[178:181], v187 offset:22528
	ds_read_b128 v[192:195], v187 offset:23552
	s_mov_b32 m0, s40
	v_lshl_add_u64 v[182:183], s[26:27], 0, v[160:161]
	global_load_lds_dwordx4 v[182:183], off
	v_lshl_add_u64 v[200:201], s[26:27], 0, v[162:163]
	s_mov_b32 m0, s41
	s_nop 0
	global_load_lds_dwordx4 v[200:201], off
	s_mov_b32 m0, s42
	v_lshl_add_u64 v[216:217], s[28:29], 0, v[160:161]
	global_load_lds_dwordx4 v[216:217], off
	v_lshl_add_u64 v[218:219], s[28:29], 0, v[162:163]
	s_mov_b32 m0, s43
	s_nop 0
	global_load_lds_dwordx4 v[218:219], off
	s_add_u32 s64, s26, 0x20000
	s_addc_u32 s65, s27, 0
	s_mov_b32 m0, s44
	v_lshl_add_u64 v[248:249], s[64:65], 0, v[160:161]
	global_load_lds_dwordx4 v[248:249], off
	v_lshl_add_u64 v[248:249], s[64:65], 0, v[162:163]
	s_mov_b32 m0, s45
	s_nop 0
	global_load_lds_dwordx4 v[248:249], off
	s_waitcnt lgkmcnt(0)
	s_nop 0
	s_barrier
	s_setprio 1
	v_mfma_f32_16x16x32_bf16 v[60:63], v[128:131], v[144:147], 0
	v_mfma_f32_16x16x32_bf16 v[56:59], v[136:139], v[144:147], 0
	v_mfma_f32_16x16x32_bf16 v[44:47], v[128:131], v[152:155], 0
	v_mfma_f32_16x16x32_bf16 v[40:43], v[136:139], v[152:155], 0
	v_mfma_f32_16x16x32_bf16 v[28:31], v[128:131], v[170:173], 0
	v_mfma_f32_16x16x32_bf16 v[24:27], v[136:139], v[170:173], 0
	v_mfma_f32_16x16x32_bf16 v[12:15], v[128:131], v[178:181], 0
	v_mfma_f32_16x16x32_bf16 v[8:11], v[136:139], v[178:181], 0
	v_mfma_f32_16x16x32_bf16 v[60:63], v[132:135], v[148:151], v[60:63]
	v_mfma_f32_16x16x32_bf16 v[56:59], v[140:143], v[148:151], v[56:59]
	v_mfma_f32_16x16x32_bf16 v[44:47], v[132:135], v[156:159], v[44:47]
	v_mfma_f32_16x16x32_bf16 v[40:43], v[140:143], v[156:159], v[40:43]
	v_mfma_f32_16x16x32_bf16 v[28:31], v[132:135], v[174:177], v[28:31]
	v_mfma_f32_16x16x32_bf16 v[24:27], v[140:143], v[174:177], v[24:27]
	v_mfma_f32_16x16x32_bf16 v[12:15], v[132:135], v[192:195], v[12:15]
	v_mfma_f32_16x16x32_bf16 v[8:11], v[140:143], v[192:195], v[8:11]
	v_mfma_f32_16x16x32_bf16 v[52:55], v[196:199], v[144:147], 0
	v_mfma_f32_16x16x32_bf16 v[48:51], v[208:211], v[144:147], 0
	v_mfma_f32_16x16x32_bf16 v[36:39], v[196:199], v[152:155], 0
	v_mfma_f32_16x16x32_bf16 v[32:35], v[208:211], v[152:155], 0
	v_mfma_f32_16x16x32_bf16 v[20:23], v[196:199], v[170:173], 0
	v_mfma_f32_16x16x32_bf16 v[16:19], v[208:211], v[170:173], 0
	v_mfma_f32_16x16x32_bf16 v[4:7], v[196:199], v[178:181], 0
	v_mfma_f32_16x16x32_bf16 v[0:3], v[208:211], v[178:181], 0
	v_mfma_f32_16x16x32_bf16 v[52:55], v[204:207], v[148:151], v[52:55]
	v_mfma_f32_16x16x32_bf16 v[48:51], v[212:215], v[148:151], v[48:51]
	v_mfma_f32_16x16x32_bf16 v[36:39], v[204:207], v[156:159], v[36:39]
	v_mfma_f32_16x16x32_bf16 v[32:35], v[212:215], v[156:159], v[32:35]
	v_mfma_f32_16x16x32_bf16 v[20:23], v[204:207], v[174:177], v[20:23]
	v_mfma_f32_16x16x32_bf16 v[16:19], v[212:215], v[174:177], v[16:19]
	v_mfma_f32_16x16x32_bf16 v[4:7], v[204:207], v[192:195], v[4:7]
	v_mfma_f32_16x16x32_bf16 v[0:3], v[212:215], v[192:195], v[0:3]
	s_setprio 0
	s_barrier
	ds_read_b128 v[128:131], v189
	ds_read_b128 v[132:135], v189 offset:1024
	ds_read_b128 v[136:139], v189 offset:2048
	ds_read_b128 v[140:143], v189 offset:3072
	s_add_u32 s28, s28, 0x20000
	s_addc_u32 s29, s29, 0
	s_mov_b32 m0, s46
	v_lshl_add_u64 v[196:197], s[28:29], 0, v[160:161]
	ds_read_b128 v[144:147], v187 offset:32768
	ds_read_b128 v[148:151], v187 offset:33792
	ds_read_b128 v[152:155], v187 offset:34816
	ds_read_b128 v[156:159], v187 offset:35840
	ds_read_b128 v[170:173], v187 offset:36864
	ds_read_b128 v[174:177], v187 offset:37888
	ds_read_b128 v[178:181], v187 offset:38912
	ds_read_b128 v[192:195], v187 offset:39936
	global_load_lds_dwordx4 v[196:197], off
	v_lshl_add_u64 v[196:197], s[28:29], 0, v[162:163]
	s_mov_b32 m0, s47
	s_nop 0
	global_load_lds_dwordx4 v[196:197], off
	ds_read_b128 v[196:199], v190
	ds_read_b128 v[204:207], v190 offset:1024
	ds_read_b128 v[208:211], v190 offset:2048
	ds_read_b128 v[212:215], v190 offset:3072
	s_waitcnt lgkmcnt(0)
	s_waitcnt vmcnt(15)
	s_barrier
	s_setprio 1
	v_mfma_f32_16x16x32_bf16 v[124:127], v[128:131], v[144:147], v[124:127]
	v_mfma_f32_16x16x32_bf16 v[120:123], v[136:139], v[144:147], v[120:123]
	v_mfma_f32_16x16x32_bf16 v[108:111], v[128:131], v[152:155], v[108:111]
	v_mfma_f32_16x16x32_bf16 v[104:107], v[136:139], v[152:155], v[104:107]
	v_mfma_f32_16x16x32_bf16 v[92:95], v[128:131], v[170:173], v[92:95]
	v_mfma_f32_16x16x32_bf16 v[88:91], v[136:139], v[170:173], v[88:91]
	v_mfma_f32_16x16x32_bf16 v[76:79], v[128:131], v[178:181], v[76:79]
	v_mfma_f32_16x16x32_bf16 v[72:75], v[136:139], v[178:181], v[72:75]
	v_mfma_f32_16x16x32_bf16 v[124:127], v[132:135], v[148:151], v[124:127]
	v_mfma_f32_16x16x32_bf16 v[120:123], v[140:143], v[148:151], v[120:123]
	v_mfma_f32_16x16x32_bf16 v[108:111], v[132:135], v[156:159], v[108:111]
	v_mfma_f32_16x16x32_bf16 v[104:107], v[140:143], v[156:159], v[104:107]
	v_mfma_f32_16x16x32_bf16 v[92:95], v[132:135], v[174:177], v[92:95]
	v_mfma_f32_16x16x32_bf16 v[88:91], v[140:143], v[174:177], v[88:91]
	v_mfma_f32_16x16x32_bf16 v[76:79], v[132:135], v[192:195], v[76:79]
	v_mfma_f32_16x16x32_bf16 v[72:75], v[140:143], v[192:195], v[72:75]
	v_mfma_f32_16x16x32_bf16 v[116:119], v[196:199], v[144:147], v[116:119]
	v_mfma_f32_16x16x32_bf16 v[112:115], v[208:211], v[144:147], v[112:115]
	v_mfma_f32_16x16x32_bf16 v[100:103], v[196:199], v[152:155], v[100:103]
	v_mfma_f32_16x16x32_bf16 v[96:99], v[208:211], v[152:155], v[96:99]
	v_mfma_f32_16x16x32_bf16 v[84:87], v[196:199], v[170:173], v[84:87]
	v_mfma_f32_16x16x32_bf16 v[80:83], v[208:211], v[170:173], v[80:83]
	v_mfma_f32_16x16x32_bf16 v[68:71], v[196:199], v[178:181], v[68:71]
	v_mfma_f32_16x16x32_bf16 v[64:67], v[208:211], v[178:181], v[64:67]
	v_mfma_f32_16x16x32_bf16 v[116:119], v[204:207], v[148:151], v[116:119]
	v_mfma_f32_16x16x32_bf16 v[112:115], v[212:215], v[148:151], v[112:115]
	v_mfma_f32_16x16x32_bf16 v[100:103], v[204:207], v[156:159], v[100:103]
	v_mfma_f32_16x16x32_bf16 v[96:99], v[212:215], v[156:159], v[96:99]
	v_mfma_f32_16x16x32_bf16 v[84:87], v[204:207], v[174:177], v[84:87]
	v_mfma_f32_16x16x32_bf16 v[80:83], v[212:215], v[174:177], v[80:83]
	v_mfma_f32_16x16x32_bf16 v[68:71], v[204:207], v[192:195], v[68:71]
	v_mfma_f32_16x16x32_bf16 v[64:67], v[212:215], v[192:195], v[64:67]
	s_setprio 0
	s_barrier
	ds_read_b128 v[144:147], v187 offset:49152
	ds_read_b128 v[148:151], v187 offset:50176
	ds_read_b128 v[152:155], v187 offset:51200
	ds_read_b128 v[156:159], v187 offset:52224
	ds_read_b128 v[170:173], v187 offset:53248
	ds_read_b128 v[174:177], v187 offset:54272
	ds_read_b128 v[178:181], v187 offset:55296
	ds_read_b128 v[192:195], v187 offset:56320
	s_mov_b32 m0, s51
	v_lshl_add_u64 v[182:183], v[182:183], 0, s[10:11]
	global_load_lds_dwordx4 v[182:183], off
	v_lshl_add_u64 v[182:183], v[200:201], 0, s[10:11]
	s_mov_b32 m0, s52
	s_nop 0
	global_load_lds_dwordx4 v[182:183], off
	s_mov_b32 m0, s53
	v_lshl_add_u64 v[182:183], v[216:217], 0, s[10:11]
	global_load_lds_dwordx4 v[182:183], off
	v_lshl_add_u64 v[182:183], v[218:219], 0, s[10:11]
	s_mov_b32 m0, s54
	s_nop 0
	global_load_lds_dwordx4 v[182:183], off
	s_add_u32 s26, s26, 0x20080
	s_addc_u32 s27, s27, 0
	s_mov_b32 m0, s55
	v_lshl_add_u64 v[248:249], s[26:27], 0, v[160:161]
	global_load_lds_dwordx4 v[248:249], off
	v_lshl_add_u64 v[248:249], s[26:27], 0, v[162:163]
	s_mov_b32 m0, s56
	s_nop 0
	global_load_lds_dwordx4 v[248:249], off
	s_waitcnt lgkmcnt(0)
	s_waitcnt vmcnt(8)
	s_barrier
	s_setprio 1
	v_mfma_f32_16x16x32_bf16 v[60:63], v[128:131], v[144:147], v[60:63]
	v_mfma_f32_16x16x32_bf16 v[56:59], v[136:139], v[144:147], v[56:59]
	v_mfma_f32_16x16x32_bf16 v[44:47], v[128:131], v[152:155], v[44:47]
	v_mfma_f32_16x16x32_bf16 v[40:43], v[136:139], v[152:155], v[40:43]
	v_mfma_f32_16x16x32_bf16 v[28:31], v[128:131], v[170:173], v[28:31]
	v_mfma_f32_16x16x32_bf16 v[24:27], v[136:139], v[170:173], v[24:27]
	v_mfma_f32_16x16x32_bf16 v[12:15], v[128:131], v[178:181], v[12:15]
	v_mfma_f32_16x16x32_bf16 v[8:11], v[136:139], v[178:181], v[8:11]
	v_mfma_f32_16x16x32_bf16 v[60:63], v[132:135], v[148:151], v[60:63]
	v_mfma_f32_16x16x32_bf16 v[56:59], v[140:143], v[148:151], v[56:59]
	v_mfma_f32_16x16x32_bf16 v[44:47], v[132:135], v[156:159], v[44:47]
	v_mfma_f32_16x16x32_bf16 v[40:43], v[140:143], v[156:159], v[40:43]
	v_mfma_f32_16x16x32_bf16 v[28:31], v[132:135], v[174:177], v[28:31]
	v_mfma_f32_16x16x32_bf16 v[24:27], v[140:143], v[174:177], v[24:27]
	v_mfma_f32_16x16x32_bf16 v[12:15], v[132:135], v[192:195], v[12:15]
	v_mfma_f32_16x16x32_bf16 v[8:11], v[140:143], v[192:195], v[8:11]
	v_mfma_f32_16x16x32_bf16 v[52:55], v[196:199], v[144:147], v[52:55]
	v_mfma_f32_16x16x32_bf16 v[48:51], v[208:211], v[144:147], v[48:51]
	v_mfma_f32_16x16x32_bf16 v[36:39], v[196:199], v[152:155], v[36:39]
	v_mfma_f32_16x16x32_bf16 v[32:35], v[208:211], v[152:155], v[32:35]
	v_mfma_f32_16x16x32_bf16 v[20:23], v[196:199], v[170:173], v[20:23]
	v_mfma_f32_16x16x32_bf16 v[16:19], v[208:211], v[170:173], v[16:19]
	v_mfma_f32_16x16x32_bf16 v[4:7], v[196:199], v[178:181], v[4:7]
	v_mfma_f32_16x16x32_bf16 v[0:3], v[208:211], v[178:181], v[0:3]
	v_mfma_f32_16x16x32_bf16 v[52:55], v[204:207], v[148:151], v[52:55]
	v_mfma_f32_16x16x32_bf16 v[48:51], v[212:215], v[148:151], v[48:51]
	v_mfma_f32_16x16x32_bf16 v[36:39], v[204:207], v[156:159], v[36:39]
	v_mfma_f32_16x16x32_bf16 v[32:35], v[212:215], v[156:159], v[32:35]
	v_mfma_f32_16x16x32_bf16 v[20:23], v[204:207], v[174:177], v[20:23]
	v_mfma_f32_16x16x32_bf16 v[16:19], v[212:215], v[174:177], v[16:19]
	v_mfma_f32_16x16x32_bf16 v[4:7], v[204:207], v[192:195], v[4:7]
	v_mfma_f32_16x16x32_bf16 v[0:3], v[212:215], v[192:195], v[0:3]
	s_setprio 0
	s_add_i32 s38, s38, 2
	s_add_u32 s24, s24, 0x100
	s_addc_u32 s25, s25, 0
	s_add_u32 s36, s36, 0x100
	s_addc_u32 s37, s37, 0
	s_cmp_gt_u32 s38, 5
	s_barrier
